# baseline (speedup 1.0000x reference)
; #define PIN(i) ((const float*)pget(p, (i)))
; __device__ __forceinline__ void phase_prep(const Params& p, int l, unsigned char* lds_g, int part, int c, int G) {
;     ...
;         const int gw = c * 8 + (tid >> 6), nw = G * 8;
;         bf16_t* XN = (bf16_t*)(ws + WS_XN);
;         const float* gain = PIN(I_NORMG) + l * 2048;
;         for (int r = gw; r < MP; r += nw) {
;             bf16_t* xo = XN + (size_t)r * 2048;
;             if (r >= TR) { for (int i = 0; i < 8; ++i) *(u32x2*)(xo + (i * 64 + lane) * 4) = (u32x2){0u, 0u}; continue; }
;     ...
;             for (int i = 0; i < 8; ++i) { const f32x4 g = *(const f32x4*)(gain + (i * 64 + lane) * 4);
.LBB0_389:
	s_add_i32 s4, s56, 6
	s_cmp_lt_u32 s4, 13
	s_cselect_b64 s[8:9], -1, 0
	s_cmp_gt_u32 s4, 12
	v_ashrrev_i32_e32 v0, 6, v18
	v_readlane_b32 s4, v249, 30
	s_cselect_b64 s[10:11], -1, 0
	s_mov_b32 s14, 5
	v_add_u32_e32 v20, s4, v0
	s_movk_i32 s4, 0x4100
	v_cmp_gt_i32_e32 vcc, s4, v20
	s_and_saveexec_b64 s[12:13], vcc
	s_cbranch_execz .LBB0_404
	v_readlane_b32 s4, v246, 35
	v_readlane_b32 s5, v246, 36
	s_lshl_b32 s4, s4, 11
	s_ashr_i32 s15, s14, 31
	s_ashr_i32 s5, s4, 31
	s_lshl_b64 s[14:15], s[14:15], 3
	s_add_u32 s14, s0, s14
	s_addc_u32 s15, s1, s15
	s_load_dwordx2 s[14:15], s[14:15], 0x0
	v_lshlrev_b32_e32 v0, 2, v18
	s_lshl_b64 s[4:5], s[4:5], 2
	s_waitcnt vmcnt(0)
	v_and_b32_e32 v2, 0xfc, v0
	v_or_b32_e32 v4, 0x400, v2
	s_waitcnt lgkmcnt(0)
	s_add_u32 s4, s14, s4
	s_addc_u32 s5, s15, s5
	v_lshlrev_b32_e32 v0, 2, v2
	v_or_b32_e32 v6, 0x500, v2
	v_lshl_add_u64 v[22:23], s[4:5], 0, v[0:1]
	v_lshlrev_b32_e32 v0, 2, v4
	v_or_b32_e32 v8, 0x600, v2
	v_lshl_add_u64 v[24:25], s[4:5], 0, v[0:1]
	v_lshlrev_b32_e32 v0, 2, v6
	v_or_b32_e32 v10, 0x700, v2
	v_lshl_add_u64 v[26:27], s[4:5], 0, v[0:1]
	v_lshlrev_b32_e32 v0, 2, v8
	v_lshl_add_u64 v[28:29], s[4:5], 0, v[0:1]
	v_lshlrev_b32_e32 v0, 2, v10
	v_ashrrev_i32_e32 v21, 31, v20
	v_lshl_add_u64 v[30:31], s[4:5], 0, v[0:1]
	v_lshlrev_b64 v[12:13], 12, v[20:21]
	v_and_b32_e32 v0, 63, v18
	v_lshl_or_b32 v12, v0, 3, v12
	v_lshl_add_u64 v[12:13], s[6:7], 0, v[12:13]
	s_mov_b64 s[4:5], 0x60a1000
	v_lshl_add_u64 v[32:33], v[12:13], 0, s[4:5]
	v_lshlrev_b64 v[34:35], 13, v[20:21]
	s_mov_b64 s[14:15], 0
	v_lshlrev_b32_e32 v0, 2, v2
	v_lshlrev_b32_e32 v36, 2, v4
	v_lshlrev_b32_e32 v38, 2, v6
	v_lshlrev_b32_e32 v40, 2, v8
	v_lshlrev_b32_e32 v42, 2, v10
	global_load_dwordx4 v[84:87], v[22:23], off offset:1024
	global_load_dwordx4 v[88:91], v[22:23], off offset:2048
	global_load_dwordx4 v[92:95], v[22:23], off offset:3072
	global_load_dwordx4 v[96:99], v[24:25], off
	global_load_dwordx4 v[100:103], v[26:27], off
	global_load_dwordx4 v[104:107], v[28:29], off
	global_load_dwordx4 v[108:111], v[30:31], off
	s_waitcnt vmcnt(0)
	s_branch .LBB0_392

; #define PIN(i) ((const float*)pget(p, (i)))
; __device__ __forceinline__ unsigned cvt_pk(float lo, float hi) { unsigned r; asm volatile("v_cvt_pk_bf16_f32 %0, %1, %2" : "=v"(r) : "v"(lo), "v"(hi)); return r; }
; __device__ __forceinline__ float wave_sum(float v) { v = sum16(v); v += __shfl_xor(v, 16); v += __shfl_xor(v, 32); return v; }
; __device__ __forceinline__ void phase_prep(const Params& p, int l, unsigned char* lds_g, int part, int c, int G) {
;     ...
;         for (int r = gw; r < MP; r += nw) {
;             bf16_t* xo = XN + (size_t)r * 2048;
;             if (r >= TR) { for (int i = 0; i < 8; ++i) *(u32x2*)(xo + (i * 64 + lane) * 4) = (u32x2){0u, 0u}; continue; }
;             const float* x = (l == 0) ? (r < TP ? PIN(I_XP) + (size_t)r * 2048 : PIN(I_XS) + (size_t)(r - TP) * 2048) : POUT + O_Y + (size_t)r * 2048;
;             f32x4 v[8]; float ss = 0.f;
; #pragma unroll
;             for (int i = 0; i < 8; ++i) { v[i] = *(const f32x4*)(x + (i * 64 + lane) * 4); ss += v[i][0] * v[i][0] + v[i][1] * v[i][1] + v[i][2] * v[i][2] + v[i][3] * v[i][3]; }
;             ss = wave_sum(ss); const float rstd = rsqrtf(ss * (1.f / 2048.f) + EPS);
; #pragma unroll
;             for (int i = 0; i < 8; ++i) { const f32x4 g = *(const f32x4*)(gain + (i * 64 + lane) * 4);
;                 u32x2 w; w.x = cvt_pk(v[i][0] * rstd * g[0], v[i][1] * rstd * g[1]); w.y = cvt_pk(v[i][2] * rstd * g[2], v[i][3] * rstd * g[3]);
;                 *(u32x2*)(xo + (i * 64 + lane) * 4) = w; }
;         }
.LBB0_401:
	v_mov_b32_e32 v37, v1
	v_mov_b32_e32 v39, v1
	v_lshl_add_u64 v[2:3], v[10:11], 0, v[36:37]
	v_lshl_add_u64 v[4:5], v[10:11], 0, v[38:39]
	v_lshl_add_u64 v[12:13], v[10:11], 0, v[0:1]
	global_load_dwordx4 v[6:9], v[2:3], off
	s_nop 0
	global_load_dwordx4 v[2:5], v[4:5], off
	s_nop 0
	global_load_dwordx4 v[44:47], v[12:13], off
	global_load_dwordx4 v[48:51], v[12:13], off offset:1024
	global_load_dwordx4 v[52:55], v[12:13], off offset:2048
	global_load_dwordx4 v[56:59], v[12:13], off offset:3072
	v_mov_b32_e32 v41, v1
	v_mov_b32_e32 v43, v1
	v_lshl_add_u64 v[12:13], v[10:11], 0, v[40:41]
	v_lshl_add_u64 v[10:11], v[10:11], 0, v[42:43]
	global_load_dwordx4 v[14:17], v[12:13], off
	s_nop 0
	global_load_dwordx4 v[10:13], v[10:11], off
	v_and_b32_e32 v19, 64, v186
	global_load_dwordx4 v[60:63], v[22:23], off
	v_xor_b32_e32 v21, 16, v186
	v_add_u32_e32 v19, 64, v19
	v_cmp_lt_i32_e32 vcc, v21, v19
	s_waitcnt vmcnt(6)
	v_mul_f32_e32 v37, v45, v45
	s_waitcnt vmcnt(5)
	v_mul_f32_e32 v39, v49, v49
	s_waitcnt vmcnt(4)
	v_mul_f32_e32 v41, v53, v53
	v_fmac_f32_e32 v37, v44, v44
	v_fmac_f32_e32 v39, v48, v48
	s_waitcnt vmcnt(3)
	v_mul_f32_e32 v43, v57, v57
	v_mov_b32_e32 v66, v7
	v_mov_b32_e32 v67, v3
	v_fmac_f32_e32 v41, v52, v52
	v_fmac_f32_e32 v37, v46, v46
	v_fmac_f32_e32 v39, v50, v50
	v_mov_b32_e32 v64, v6
	v_mov_b32_e32 v65, v2
	v_fmac_f32_e32 v43, v56, v56
	v_pk_mul_f32 v[66:67], v[66:67], v[66:67]
	v_fmac_f32_e32 v41, v54, v54
	v_fmac_f32_e32 v37, v47, v47
	v_fmac_f32_e32 v39, v51, v51
	s_waitcnt vmcnt(2)
	v_mov_b32_e32 v70, v15
	s_waitcnt vmcnt(1)
	v_mov_b32_e32 v71, v11
	v_mov_b32_e32 v72, v8
	v_mov_b32_e32 v73, v4
	v_fmac_f32_e32 v43, v58, v58
	v_pk_fma_f32 v[64:65], v[64:65], v[64:65], v[66:67]
	v_fmac_f32_e32 v41, v55, v55
	v_add_f32_e32 v37, v37, v39
	v_mov_b32_e32 v68, v14
	v_mov_b32_e32 v69, v10
	v_mov_b32_e32 v76, v9
	v_mov_b32_e32 v77, v5
	v_pk_mul_f32 v[70:71], v[70:71], v[70:71]
	v_fmac_f32_e32 v43, v59, v59
	v_pk_fma_f32 v[64:65], v[72:73], v[72:73], v[64:65]
	v_add_f32_e32 v37, v37, v41
	v_mov_b32_e32 v74, v16
	v_mov_b32_e32 v75, v12
	v_pk_fma_f32 v[66:67], v[68:69], v[68:69], v[70:71]
	v_pk_fma_f32 v[64:65], v[76:77], v[76:77], v[64:65]
	v_add_f32_e32 v37, v37, v43
	v_mov_b32_e32 v78, v17
	v_mov_b32_e32 v79, v13
	v_pk_fma_f32 v[66:67], v[74:75], v[74:75], v[66:67]
	v_add_f32_e32 v37, v37, v64
	v_pk_fma_f32 v[66:67], v[78:79], v[78:79], v[66:67]
	v_add_f32_e32 v37, v37, v65
	v_add_f32_e32 v37, v37, v66
	v_add_f32_e32 v37, v37, v67
	v_cndmask_b32_e32 v21, v186, v21, vcc
	v_lshlrev_b32_e32 v21, 2, v21
	v_add_f32_dpp v37, v37, v37 quad_perm:[1,0,3,2] row_mask:0xf bank_mask:0xf bound_ctrl:1
	v_xor_b32_e32 v39, 32, v186
	v_cmp_lt_i32_e32 vcc, v39, v19
	v_add_f32_dpp v37, v37, v37 quad_perm:[2,3,0,1] row_mask:0xf bank_mask:0xf bound_ctrl:1
	s_nop 0
	v_cndmask_b32_e32 v19, v186, v39, vcc
	v_add_f32_dpp v37, v37, v37 row_half_mirror row_mask:0xf bank_mask:0xf bound_ctrl:1
	v_lshlrev_b32_e32 v19, 2, v19
	s_nop 0
	v_add_f32_dpp v37, v37, v37 row_mirror row_mask:0xf bank_mask:0xf bound_ctrl:1
	ds_bpermute_b32 v21, v21, v37
	s_waitcnt lgkmcnt(0)
	v_add_f32_e32 v21, v37, v21
	ds_bpermute_b32 v19, v19, v21
	s_waitcnt lgkmcnt(0)
	v_add_f32_e32 v19, v21, v19
	v_fmamk_f32 v19, v19, 0x3a000000, v158
	v_mul_f32_e32 v21, 0x4b800000, v19
	v_cmp_gt_f32_e32 vcc, s93, v19
	s_nop 1
	v_cndmask_b32_e32 v19, v19, v21, vcc
	v_rsq_f32_e32 v19, v19
	s_nop 0
	v_mul_f32_e32 v21, 0x45800000, v19
	v_cndmask_b32_e32 v19, v19, v21, vcc
	v_mul_f32_e32 v21, v44, v19
	v_mul_f32_e32 v37, v45, v19
	v_mul_f32_e32 v39, v46, v19
	v_mul_f32_e32 v41, v47, v19
	s_waitcnt vmcnt(0)
	v_mul_f32_e32 v21, v60, v21
	v_mul_f32_e32 v37, v61, v37
	v_mul_f32_e32 v39, v62, v39
	v_mul_f32_e32 v41, v63, v41
	v_cvt_pk_bf16_f32 v44, v21, v37
	v_cvt_pk_bf16_f32 v45, v39, v41
	global_store_dwordx2 v[32:33], v[44:45], off
	s_nop 1
	v_mov_b64_e32 v[44:45], v[84:85]
	v_mov_b64_e32 v[46:47], v[86:87]
	v_mul_f32_e32 v21, v48, v19
	v_mul_f32_e32 v37, v49, v19
	v_mul_f32_e32 v39, v50, v19
	v_mul_f32_e32 v41, v51, v19
	v_mul_f32_e32 v6, v6, v19
	v_mul_f32_e32 v7, v7, v19
	v_mul_f32_e32 v8, v8, v19
	v_mul_f32_e32 v9, v9, v19
	v_mul_f32_e32 v2, v2, v19
	v_mul_f32_e32 v3, v3, v19
	v_mul_f32_e32 v4, v4, v19
	v_mul_f32_e32 v5, v5, v19
	v_mul_f32_e32 v21, v44, v21
	v_mul_f32_e32 v37, v45, v37
	v_mul_f32_e32 v39, v46, v39
	v_mul_f32_e32 v41, v47, v41
	v_cvt_pk_bf16_f32 v44, v21, v37
	v_cvt_pk_bf16_f32 v45, v39, v41
	global_store_dwordx2 v[32:33], v[44:45], off offset:512
	s_nop 1
	v_mov_b64_e32 v[44:45], v[88:89]
	v_mov_b64_e32 v[46:47], v[90:91]
	v_mul_f32_e32 v21, v52, v19
	v_mul_f32_e32 v37, v53, v19
	v_mul_f32_e32 v39, v54, v19
	v_mul_f32_e32 v41, v55, v19
	v_mul_f32_e32 v21, v44, v21
	v_mul_f32_e32 v37, v45, v37
	v_mul_f32_e32 v39, v46, v39
	v_mul_f32_e32 v41, v47, v41
	v_cvt_pk_bf16_f32 v44, v21, v37
	v_cvt_pk_bf16_f32 v45, v39, v41
	global_store_dwordx2 v[32:33], v[44:45], off offset:1024
	s_nop 1
	v_mov_b64_e32 v[44:45], v[92:93]
	v_mov_b64_e32 v[46:47], v[94:95]
	v_mul_f32_e32 v21, v56, v19
	v_mul_f32_e32 v37, v57, v19
	v_mul_f32_e32 v39, v58, v19
	v_mul_f32_e32 v41, v59, v19
	v_mul_f32_e32 v21, v21, v44
	v_mul_f32_e32 v37, v37, v45
	v_mul_f32_e32 v39, v39, v46
	v_mul_f32_e32 v41, v41, v47
	v_cvt_pk_bf16_f32 v44, v21, v37
	v_cvt_pk_bf16_f32 v45, v39, v41
	global_store_dwordx2 v[32:33], v[44:45], off offset:1536
	s_nop 1
	v_mov_b64_e32 v[44:45], v[96:97]
	v_mov_b64_e32 v[46:47], v[98:99]
	v_mul_f32_e32 v6, v6, v44
	v_mul_f32_e32 v7, v7, v45
	v_mul_f32_e32 v8, v8, v46
	v_mul_f32_e32 v9, v9, v47
	v_cvt_pk_bf16_f32 v6, v6, v7
	v_cvt_pk_bf16_f32 v7, v8, v9
	global_store_dwordx2 v[32:33], v[6:7], off offset:2048
	s_nop 1
	v_mov_b64_e32 v[6:7], v[100:101]
	v_mov_b64_e32 v[8:9], v[102:103]
	v_mul_f32_e32 v2, v2, v6
	v_mul_f32_e32 v3, v3, v7
	v_mul_f32_e32 v4, v4, v8
	v_mul_f32_e32 v5, v5, v9
	v_cvt_pk_bf16_f32 v2, v2, v3
	v_cvt_pk_bf16_f32 v3, v4, v5
	global_store_dwordx2 v[32:33], v[2:3], off offset:2560
	s_nop 1
	v_mov_b64_e32 v[2:3], v[104:105]
	v_mov_b64_e32 v[4:5], v[106:107]
	v_mul_f32_e32 v6, v14, v19
	v_mul_f32_e32 v7, v15, v19
	v_mul_f32_e32 v8, v16, v19
	v_mul_f32_e32 v9, v17, v19
	v_mul_f32_e32 v2, v6, v2
	v_mul_f32_e32 v3, v7, v3
	v_mul_f32_e32 v4, v8, v4
	v_mul_f32_e32 v5, v9, v5
	v_cvt_pk_bf16_f32 v2, v2, v3
	v_cvt_pk_bf16_f32 v3, v4, v5
	global_store_dwordx2 v[32:33], v[2:3], off offset:3072
	s_nop 1
	v_mov_b64_e32 v[2:3], v[108:109]
	v_mov_b64_e32 v[4:5], v[110:111]
	v_mul_f32_e32 v6, v10, v19
	v_mul_f32_e32 v7, v11, v19
	v_mul_f32_e32 v8, v12, v19
	v_mul_f32_e32 v9, v13, v19
	v_mul_f32_e32 v2, v6, v2
	v_mul_f32_e32 v3, v7, v3
	v_mul_f32_e32 v4, v8, v4
	v_mul_f32_e32 v5, v9, v5
	v_cvt_pk_bf16_f32 v2, v2, v3
	v_cvt_pk_bf16_f32 v3, v4, v5
	global_store_dwordx2 v[32:33], v[2:3], off offset:3584
